# PAPR second-round tile pairs split three ways across workgroups c, c+32, c+64 (per-workgroup start/stride/bound of the static unit progression, T handed over by release/acquire flags)
# speedup vs baseline: 1.0115x; 1.0104x over previous
.LBB0_1381:
	s_mov_b32 s87, 0
	s_cmp_lg_u32 s94, 0x100
	s_cbranch_scc1 .Lp3_a_done
	s_cmp_lt_u32 s34, 64
	s_cbranch_scc1 .Lp3_a_done
	s_cmp_ge_u32 s34, 96
	s_cbranch_scc1 .Lp3_a_done
	s_sub_u32 s34, s34, 32
	s_mov_b32 s87, 1
.Lp3_a_done:
	s_add_u32 s6, s50, 0xff05000
	s_addc_u32 s7, s51, 0
	s_add_u32 s8, s50, 0x14705000
	s_addc_u32 s9, s51, 0
	s_add_u32 s2, s50, 0x7004000
	s_addc_u32 s3, s51, 0
	s_ashr_i32 s33, s34, 31
	v_mov_b32_e32 v9, v128
	s_cmpk_lt_i32 s34, 0x120
	s_cselect_b64 s[12:13], -1, 0
	s_cmpk_gt_i32 s34, 0x11f
	v_readfirstlane_b32 s4, v9
	s_cbranch_scc1 .LBB0_1397
	s_cmp_lg_u32 s94, 0x100
	s_cbranch_scc1 .Lp3_b_done
	s_cmp_eq_u32 s87, 1
	s_cbranch_scc1 .Lp3_b_done
	s_cmp_lt_u32 s34, 32
	s_cbranch_scc1 .Lp3_b_done
	s_cmp_lt_u32 s34, 64
	s_cbranch_scc1 .LBB0_1397
.Lp3_b_done:
	v_lshlrev_b32_e32 v0, 4, v9
	v_add_u32_e32 v1, 0x2000, v0
	s_waitcnt vmcnt(0)
	v_ashrrev_i32_e32 v2, 31, v1
	v_lshrrev_b32_e32 v2, 22, v2
	v_add_u32_e32 v2, v1, v2
	v_ashrrev_i32_e32 v8, 10, v2
	v_mul_i32_i24_e32 v2, 0x400, v8
	v_sub_u32_e32 v1, v1, v2
	v_lshrrev_b32_e32 v2, 4, v1
	v_bitop3_b32 v1, v2, v1, 32 bitop3:0x6c
	v_ashrrev_i32_e32 v2, 31, v1
	v_lshrrev_b32_e32 v2, 26, v2
	v_add_u32_e32 v2, v1, v2
	v_lshlrev_b32_e32 v3, 3, v8
	v_ashrrev_i32_e32 v10, 6, v2
	v_and_b32_e32 v3, -16, v3
	v_add_u32_e32 v3, v10, v3
	v_and_b32_e32 v4, 3, v10
	s_mov_b32 s10, 0x1fffe0
	v_lshrrev_b32_e32 v5, 2, v3
	v_lshlrev_b32_e32 v6, 1, v3
	v_and_b32_e32 v2, 0xc0, v2
	v_and_or_b32 v4, v3, s10, v4
	v_and_b32_e32 v5, 4, v5
	v_and_b32_e32 v6, 24, v6
	v_sub_u32_e32 v1, v1, v2
	v_mov_b32_e32 v2, 1
	v_or3_b32 v4, v4, v5, v6
	v_lshlrev_b32_e32 v5, 5, v8
	v_ashrrev_i16_sdwa v1, v2, sext(v1) dst_sel:DWORD dst_unused:UNUSED_PAD src0_sel:DWORD src1_sel:BYTE_0
	v_and_b32_e32 v5, 32, v5
	v_bfe_i32 v11, v1, 0, 16
	v_add_lshl_u32 v1, v5, v11, 1
	v_lshl_add_u32 v130, v4, 11, v1
	v_lshl_add_u32 v132, v3, 11, v1
	v_bfe_i32 v1, v9, 27, 1
	v_lshrrev_b32_e32 v1, 22, v1
	v_add_u32_e32 v1, v0, v1
	v_and_b32_e32 v1, 0xfffffc00, v1
	v_sub_u32_e32 v0, v0, v1
	v_lshrrev_b32_e32 v1, 4, v0
	v_ashrrev_i32_e32 v3, 31, v9
	v_bitop3_b32 v0, v1, v0, 32 bitop3:0x6c
	v_lshrrev_b32_e32 v3, 26, v3
	v_ashrrev_i32_e32 v1, 31, v0
	v_add_u32_e32 v3, v9, v3
	v_lshrrev_b32_e32 v1, 26, v1
	v_ashrrev_i32_e32 v13, 6, v3
	v_add_u32_e32 v1, v0, v1
	v_lshlrev_b32_e32 v3, 3, v13
	v_ashrrev_i32_e32 v12, 6, v1
	v_and_b32_e32 v3, -16, v3
	v_add_u32_e32 v3, v12, v3
	v_and_b32_e32 v4, 3, v12
	s_add_u32 s35, s50, 0x21605000
	v_and_or_b32 v4, v3, s10, v4
	s_mul_hi_i32 s10, s34, 0x38e38e39
	s_addc_u32 s60, s51, 0
	s_lshr_b32 s11, s10, 31
	s_ashr_i32 s10, s10, 6
	s_add_i32 s10, s10, s11
	s_mul_i32 s15, s10, 0xfffffee0
	s_add_i32 s15, s15, s34
	s_ashr_i32 s16, s15, 31
	s_lshr_b32 s16, s16, 29
	s_add_i32 s16, s15, s16
	s_ashr_i32 s14, s4, 6
	s_ashr_i32 s17, s16, 3
	s_and_b32 s16, s16, -8
	s_ashr_i32 s5, s4, 8
	s_lshl_b32 s61, s14, 10
	s_ashr_i32 s11, s10, 31
	s_sub_i32 s15, s15, s16
	s_cmp_lt_i32 s15, 0
	s_cselect_b32 s16, 37, 36
	s_mul_i32 s15, s16, s15
	s_add_i32 s15, s15, s17
	s_ashr_i32 s16, s15, 31
	s_lshr_b32 s16, s16, 26
	s_add_i32 s16, s15, s16
	s_ashr_i32 s17, s16, 6
	s_lshl_b32 s17, s17, 3
	v_and_b32_e32 v1, 0xc0, v1
	s_sub_i32 s18, 36, s17
	v_sub_u32_e32 v0, v0, v1
	s_min_i32 s18, s18, 8
	v_ashrrev_i16_sdwa v0, v2, sext(v0) dst_sel:DWORD dst_unused:UNUSED_PAD src0_sel:DWORD src1_sel:BYTE_0
	s_abs_i32 s19, s18
	v_bfe_i32 v14, v0, 0, 16
	v_cvt_f32_u32_e32 v0, s19
	s_sub_i32 s21, 0, s19
	s_andn2_b32 s16, s16, 63
	s_sub_i32 s15, s15, s16
	v_rcp_iflag_f32_e32 v0, v0
	s_abs_i32 s20, s15
	s_xor_b32 s16, s15, s18
	s_ashr_i32 s16, s16, 31
	v_mul_f32_e32 v0, 0x4f7ffffe, v0
	v_cvt_u32_f32_e32 v0, v0
	v_lshrrev_b32_e32 v5, 2, v3
	v_lshlrev_b32_e32 v6, 1, v3
	v_and_b32_e32 v5, 4, v5
	v_readfirstlane_b32 s22, v0
	s_mul_i32 s21, s21, s22
	s_mul_hi_u32 s21, s22, s21
	s_add_i32 s22, s22, s21
	s_mul_hi_u32 s21, s20, s22
	s_mul_i32 s22, s21, s19
	s_sub_i32 s20, s20, s22
	s_add_i32 s22, s21, 1
	s_sub_i32 s23, s20, s19
	s_cmp_ge_u32 s20, s19
	s_cselect_b32 s21, s22, s21
	s_cselect_b32 s20, s23, s20
	s_add_i32 s22, s21, 1
	s_cmp_ge_u32 s20, s19
	s_cselect_b32 s19, s22, s21
	s_xor_b32 s19, s19, s16
	s_sub_i32 s30, s19, s16
	s_mul_i32 s16, s30, s18
	s_sub_i32 s15, s15, s16
	s_add_i32 s52, s15, s17
	s_ashr_i32 s53, s52, 31
	s_lshl_b64 s[10:11], s[10:11], 11
	s_lshl_b64 s[16:17], s[52:53], 19
	s_add_u32 s15, s35, s16
	s_addc_u32 s18, s60, s17
	s_ashr_i32 s31, s30, 31
	s_lshl_b64 s[16:17], s[30:31], 19
	v_and_b32_e32 v6, 24, v6
	s_add_u32 s16, s2, s16
	v_or3_b32 v4, v4, v5, v6
	v_lshlrev_b32_e32 v5, 5, v13
	s_addc_u32 s17, s3, s17
	v_and_b32_e32 v5, 32, v5
	s_add_u32 s56, s16, s10
	v_add_lshl_u32 v1, v5, v14, 1
	s_addc_u32 s57, s17, s11
	s_add_i32 s31, s61, 0
	v_lshl_add_u32 v134, v4, 11, v1
	s_add_i32 m0, s31, 0x10000
	v_lshl_add_u32 v136, v3, 11, v1
	global_load_lds_dwordx4 v134, s[56:57]
	s_add_i32 m0, s31, 0x12000
	s_add_u32 s16, s56, 0x40000
	global_load_lds_dwordx4 v130, s[56:57]
	s_addc_u32 s17, s57, 0
	s_add_i32 m0, s31, 0x14000
	v_mov_b32_e32 v135, 0
	global_load_lds_dwordx4 v134, s[16:17]
	s_add_i32 m0, s31, 0x16000
	s_add_u32 s54, s15, s10
	s_addc_u32 s55, s18, s11
	s_add_i32 s53, s31, 0x2000
	global_load_lds_dwordx4 v130, s[16:17]
	s_mov_b32 m0, s31
	s_add_u32 s10, s54, 0x40000
	global_load_lds_dwordx4 v136, s[54:55]
	s_mov_b32 m0, s53
	s_addc_u32 s11, s55, 0
	s_add_i32 s62, s31, 0x4000
	global_load_lds_dwordx4 v132, s[54:55]
	s_mov_b32 m0, s62
	s_add_i32 s63, s31, 0x6000
	global_load_lds_dwordx4 v136, s[10:11]
	s_mov_b32 m0, s63
	v_mov_b32_e32 v131, v135
	global_load_lds_dwordx4 v132, s[10:11]
	v_mov_b32_e32 v137, v135
	v_mov_b32_e32 v133, v135
	s_cmp_eq_u32 s5, 1
	s_mov_b32 s64, 0
	v_lshl_add_u64 v[6:7], s[56:57], 0, v[134:135]
	v_lshl_add_u64 v[4:5], s[56:57], 0, v[130:131]
	v_lshl_add_u64 v[0:1], s[54:55], 0, v[136:137]
	s_cselect_b64 s[10:11], -1, 0
	s_cmp_lg_u32 s5, 1
	v_lshl_add_u64 v[2:3], s[54:55], 0, v[132:133]
	s_cbranch_scc1 .LBB0_1384
	s_barrier
.LBB0_1384:
	s_lshl_b32 s14, s14, 5
	s_and_b32 s19, s14, 0x60
	s_mov_b64 s[14:15], 0x80
	s_add_i32 m0, s31, 0x18000
	v_lshl_add_u64 v[6:7], v[6:7], 0, s[14:15]
	s_lshl_b32 s18, s5, 13
	s_lshl_b32 s20, s19, 7
	s_waitcnt vmcnt(2)
	s_barrier
	global_load_lds_dwordx4 v[6:7], off
	v_lshl_add_u64 v[4:5], v[4:5], 0, s[14:15]
	s_add_i32 m0, s31, 0x1a000
	s_add_i32 s65, s31, 0x8000
	s_add_i32 s66, s31, 0xa000
	global_load_lds_dwordx4 v[4:5], off
	v_lshl_add_u64 v[0:1], v[0:1], 0, s[14:15]
	s_mov_b32 m0, s65
	s_add_u32 s16, s56, 0x40080
	global_load_lds_dwordx4 v[0:1], off
	v_lshl_add_u64 v[0:1], v[2:3], 0, s[14:15]
	s_mov_b32 m0, s66
	s_addc_u32 s17, s57, 0
	global_load_lds_dwordx4 v[0:1], off
	s_add_i32 m0, s31, 0x1c000
	v_lshl_add_u64 v[0:1], s[16:17], 0, v[134:135]
	global_load_lds_dwordx4 v[0:1], off
	v_lshl_add_u64 v[0:1], s[16:17], 0, v[130:131]
	s_add_i32 m0, s31, 0x1e000
	s_cmpk_lt_u32 s4, 0x100
	global_load_lds_dwordx4 v[0:1], off
	v_lshrrev_b32_e32 v1, 1, v9
	v_and_b32_e32 v1, 24, v1
	v_and_b32_e32 v0, 15, v9
	v_lshlrev_b32_e32 v2, 1, v1
	v_lshl_or_b32 v129, s5, 6, v0
	v_lshl_or_b32 v0, v0, 6, v2
	v_lshlrev_b32_e32 v2, 2, v9
	v_and_b32_e32 v2, 32, v2
	v_bitop3_b32 v3, v0, s18, v2 bitop3:0xde
	v_bitop3_b32 v156, v0, s20, v2 bitop3:0xde
	v_lshlrev_b32_e32 v0, 14, v13
	v_and_b32_e32 v0, 0xffff8000, v0
	v_or_b32_e32 v157, s19, v1
	v_lshl_add_u32 v0, v12, 11, v0
	v_and_b32_e32 v1, 1, v13
	v_lshl_or_b32 v0, v1, 6, v0
	v_lshl_add_u32 v138, v14, 1, v0
	v_lshlrev_b32_e32 v0, 14, v8
	v_and_b32_e32 v0, 0xffff8000, v0
	s_waitcnt vmcnt(6)
	v_lshl_add_u32 v0, v10, 11, v0
	v_and_b32_e32 v1, 1, v8
	s_cselect_b64 s[16:17], -1, 0
	v_lshl_or_b32 v0, v1, 6, v0
	s_add_i32 s69, 0, 0x10000
	s_add_i32 s70, 0, 0x14000
	s_ashr_i32 s67, s94, 31
	s_mov_b32 s68, s94
	v_mov_b32_e32 v139, v135
	v_lshl_add_u32 v140, v11, 1, v0
	v_mov_b32_e32 v141, v135
	v_mov_b64_e32 v[142:143], 0x120
	v_mov_b64_e32 v[144:145], 0x11f
	s_cmp_eq_u32 s87, 1
	s_cbranch_scc0 .Lp3_c_done
	s_movk_i32 s68, 32
	s_add_u32 s84, s34, 32
	v_mov_b32_e32 v144, s84
	v_mov_b32_e32 v145, 0
	s_add_u32 s84, s84, 1
	v_mov_b32_e32 v142, s84
	v_mov_b32_e32 v143, 0
.Lp3_c_done:
	v_add_u32_e32 v158, s69, v156
	v_add_u32_e32 v159, s70, v156
	v_add_u32_e32 v160, 0, v3
	s_movk_i32 s71, 0x5c00
	s_mov_b64 s[18:19], 0x3c00
	s_movk_i32 s72, 0x3000
	s_barrier
	s_branch .LBB0_1387

.LBB0_1396:
	s_waitcnt vmcnt(0)
	s_barrier
	s_cmp_lg_u32 s94, 0x100
	s_cbranch_scc1 .Lpapr_noflag
	s_cmp_ge_u32 s34, 64
	s_cbranch_scc1 .Lpapr_noflag
	v_cmp_eq_u32_e32 vcc, 0, v128
	s_and_saveexec_b64 s[84:85], vcc
	s_cbranch_execz .Lpapr_flagdone
	buffer_wbl2 sc1
	s_waitcnt vmcnt(0)
	s_lshl_b32 s86, s34, 2
	v_mov_b32_e32 v252, s86
	v_mov_b32_e32 v253, 1
	global_atomic_add v252, v253, s[50:51]
.Lpapr_flagdone:
	s_or_b64 exec, exec, s[84:85]
	s_cmp_eq_u32 s87, 1
	s_cbranch_scc0 .Lpapr_noflag
	s_add_u32 s34, s34, 32
	s_mov_b32 s87, 0

.LBB0_1409:
	s_cmp_lg_u32 s94, 0x100
	s_cbranch_scc1 .Lpapr_nowait
	s_cmp_lt_u32 s34, 32
	s_cbranch_scc1 .Lpapr_nowait
	s_cmp_ge_u32 s34, 64
	s_cbranch_scc1 .Lpapr_nowait
	s_mov_b32 s84, s34
	s_cmp_eq_u32 s66, 1
	s_cbranch_scc1 .Lpapr_poll0
	s_sub_u32 s84, s34, 32
.Lpapr_poll0:
	s_lshl_b32 s84, s84, 2
	v_mov_b32_e32 v252, s84

.LBB0_1413:
	s_abs_i32 s4, s94
	v_cvt_f32_u32_e32 v0, s4
	s_sub_i32 s5, 0, s4
	v_rcp_iflag_f32_e32 v0, v0
	s_nop 0
	v_mul_f32_e32 v0, 0x4f7ffffe, v0
	v_cvt_u32_f32_e32 v0, v0
	s_nop 0
	v_readfirstlane_b32 s6, v0
	s_mul_i32 s5, s5, s6
	s_mul_hi_u32 s5, s6, s5
	s_add_i32 s6, s6, s5
	s_mul_hi_u32 s5, s6, 0x120
	s_mul_i32 s5, s5, s4
	s_sub_i32 s5, 0x120, s5
	s_sub_i32 s6, s5, s4
	s_cmp_ge_u32 s5, s4
	s_cselect_b32 s5, s6, s5
	s_sub_i32 s6, s5, s4
	s_cmp_ge_u32 s5, s4
	s_cselect_b32 s6, s6, s5
	s_cmp_lg_u32 s94, 0x100
	s_cbranch_scc1 .Lpapr_rem_done
	s_movk_i32 s6, 96
